# attention selected-block loop: two K/V tiles in flight (tile t+2 requested at the top of iteration t into alternating landing registers, copied to the staging registers at the end of the iteration)
# speedup vs baseline: 1.0007x; 1.0007x over previous
; DI void hsync() { hsync_impl(false); }
; DI void kv_commit(const KVRegs& r, u16* Ks, u16* Vts, int tid) {
; #pragma unroll
;   for (int i = 0; i < 2; ++i) {
;     int c = tid + 256 * i;
;     int row = c >> 3, ch = (c & 7) * 8;
;     *(u32x4*)(Ks + row * 72 + ch) = r.k[i];
;     *(u32x4*)(Vts + row * 72 + ch) = r.v[i];
;   }
;   hsync();
; DI void attn_item(const Params& p, int item, char* smem) {
;     ...
;     if (am) { j = __builtin_ctzll(am); am &= am - 1; }
;     if (j >= 0) kv_issue(kvr, KS + ((size_t)(b * 4096 + 64 * j)) * 128 + g * 64, 128, VTS + (size_t)bg * 64 * 4096 + 64 * j, 4096, tid);
; #pragma unroll 1
;     while (j >= 0) {
;       kv_commit(kvr, Ks, Vts, tid);
;       int jn = -1;
;       if (am) { jn = __builtin_ctzll(am); am &= am - 1; }
;       if (jn >= 0) kv_issue(kvr, KS + ((size_t)(b * 4096 + 64 * jn)) * 128 + g * 64, 128, VTS + (size_t)bg * 64 * 4096 + 64 * jn, 4096, tid);
;       bool ls = (j < 32) ? ((mylo >> j) & 1u) : ((myhi >> (j - 32)) & 1u);
;       if (j < qb) attend_tile<1, false, 2, 0>(Ks, Vts, qf, O, m, l, t - 64 * j, slope2, ls, 0.f, nullptr, 0, lr, hh);
;       else attend_tile<1, false, 1, 0>(Ks, Vts, qf, O, m, l, t - 64 * j, slope2, ls, 0.f, nullptr, 0, lr, hh);
;       pb ^= 1;
;       j = jn;
;     }
.LBB0_630:
	s_add_u32 s10, s0, -1
	s_addc_u32 s11, s1, -1
	s_and_b64 s[88:89], s[10:11], s[0:1]
	s_lshl_b64 s[0:1], s[8:9], 1
	v_readlane_b32 s10, v253, 63
	s_add_u32 s0, s10, s0
	v_readlane_b32 s10, v252, 0
	s_addc_u32 s1, s10, s1
	s_lshl_b32 s10, s91, 13
	s_mov_b32 s58, s57
	v_readlane_b32 s57, v252, 1
	s_add_u32 s90, s57, s10
	v_readlane_b32 s57, v252, 2
	s_addc_u32 s91, s57, 0
	v_mov_b32_e32 v57, v97
	v_mov_b32_e32 v168, 0
	s_mov_b32 s11, s18
	s_mov_b32 s57, s58
	v_lshl_add_u64 v[118:119], s[0:1], 0, v[56:57]
	v_lshl_add_u64 v[120:121], s[90:91], 0, v[56:57]
	v_sub_u32_e32 v57, v157, v116
	v_mov_b32_e32 v169, 0xf149f2ca
	v_mov_b32_e32 v122, 0
	v_mov_b32_e32 v123, v168
	v_mov_b32_e32 v124, 0
	v_mov_b32_e32 v125, v168
	v_mov_b32_e32 v126, 0
	v_mov_b32_e32 v127, v168
	v_mov_b32_e32 v128, 0
	v_mov_b32_e32 v129, v168
	v_mov_b32_e32 v130, 0
	v_mov_b32_e32 v131, v168
	v_mov_b32_e32 v132, 0
	v_mov_b32_e32 v133, v168
	v_mov_b32_e32 v134, 0
	v_mov_b32_e32 v135, v168
	v_mov_b32_e32 v136, 0
	v_mov_b32_e32 v137, v168
	v_mov_b32_e32 v138, 0
	v_mov_b32_e32 v139, v168
	v_mov_b32_e32 v140, 0
	v_mov_b32_e32 v141, v168
	v_mov_b32_e32 v142, 0
	v_mov_b32_e32 v143, v168
	v_mov_b32_e32 v144, 0
	v_mov_b32_e32 v145, v168
	v_mov_b32_e32 v146, 0
	v_mov_b32_e32 v147, v168
	v_mov_b32_e32 v148, 0
	v_mov_b32_e32 v149, v168
	v_mov_b32_e32 v150, 0
	v_mov_b32_e32 v151, v168
	v_mov_b32_e32 v152, 0
	v_mov_b32_e32 v153, v168
	s_ff1_i32_b64 s100, s[88:89]
	s_cmp_lg_u64 s[88:89], 0
	s_cselect_b32 s100, s100, 0
	s_lshl_b32 s1, s100, 6
	s_add_i32 vcc_lo, s1, s38
	s_mov_b32 vcc_hi, s18
	s_lshl_b64 vcc, vcc, 8
	v_lshl_add_u64 v[0:1], v[118:119], 0, vcc
	s_lshl_b32 s0, s100, 7
	s_mov_b32 s1, s18
	v_lshl_add_u64 v[2:3], v[120:121], 0, s[0:1]
	v_lshl_add_u64 v[4:5], v[0:1], 0, v[108:109]
	v_lshl_add_u64 v[0:1], v[0:1], 0, v[110:111]
	v_lshl_add_u64 v[6:7], v[2:3], 0, v[58:59]
	v_lshl_add_u64 v[2:3], v[2:3], 0, v[60:61]
	s_cmp_eq_u32 s79, 0
	s_cbranch_scc0 .Lkvd_p0
	global_load_dwordx4 v[222:225], v[4:5], off
	global_load_dwordx4 v[226:229], v[6:7], off
	global_load_dwordx4 v[230:233], v[0:1], off
	global_load_dwordx4 v[234:237], v[2:3], off
	s_branch .Lkvd_p1
.Lkvd_p0:
	global_load_dwordx4 v[200:203], v[4:5], off
	global_load_dwordx4 v[204:207], v[6:7], off
	global_load_dwordx4 v[214:217], v[0:1], off
	global_load_dwordx4 v[218:221], v[2:3], off
.Lkvd_p1:
.LBB0_631:
	s_mul_i32 s0, s79, 0x4800
	s_add_i32 s81, s33, s0
	v_lshl_add_u32 v0, v100, 1, s81
	v_lshl_add_u32 v1, v158, 1, v0
	v_lshl_add_u32 v0, v159, 1, v0
	s_waitcnt vmcnt(7)
	ds_write_b128 v1, v[80:83]
	s_waitcnt vmcnt(6)
	ds_write_b128 v1, v[84:87] offset:9216
	s_waitcnt vmcnt(5)
	ds_write_b128 v0, v[88:91]
	s_waitcnt vmcnt(4)
	ds_write_b128 v0, v[92:95] offset:9216
	s_waitcnt lgkmcnt(0)
	v_add_u32_e32 v251, 1, v251
	ds_write_b32 v249, v251
.Lfhs_0:
	ds_read_b128 v[244:247], v250
	s_waitcnt lgkmcnt(0)
	v_min3_u32 v248, v244, v245, v246
	v_min_u32_e32 v248, v248, v247
	v_cmp_ge_u32_e32 vcc, v248, v251
	s_cbranch_vccz .Lfhs_0
	s_ff1_i32_b64 s92, s[88:89]
	s_cmp_lg_u64 s[88:89], 0
	s_cselect_b32 s0, s92, -1
	s_cmp_lt_i32 s0, 0
	s_cselect_b64 s[90:91], -1, 0
	s_add_u32 s98, s88, -1
	s_addc_u32 s99, s89, -1
	s_and_b64 s[98:99], s[98:99], s[88:89]
	s_ff1_i32_b64 s100, s[98:99]
	s_cmp_lg_u64 s[98:99], 0
	s_cselect_b32 s100, s100, 0
	s_lshl_b32 s1, s100, 6
	s_add_i32 vcc_lo, s1, s38
	s_mov_b32 vcc_hi, s18
	s_lshl_b64 vcc, vcc, 8
	v_lshl_add_u64 v[0:1], v[118:119], 0, vcc
	s_lshl_b32 s0, s100, 7
	s_mov_b32 s1, s18
	v_lshl_add_u64 v[2:3], v[120:121], 0, s[0:1]
	v_lshl_add_u64 v[4:5], v[0:1], 0, v[108:109]
	v_lshl_add_u64 v[0:1], v[0:1], 0, v[110:111]
	v_lshl_add_u64 v[6:7], v[2:3], 0, v[58:59]
	v_lshl_add_u64 v[2:3], v[2:3], 0, v[60:61]
	s_cmp_eq_u32 s79, 0
	s_cbranch_scc0 .Lkvd_l1
	global_load_dwordx4 v[200:203], v[4:5], off
	global_load_dwordx4 v[204:207], v[6:7], off
	global_load_dwordx4 v[214:217], v[0:1], off
	global_load_dwordx4 v[218:221], v[2:3], off
	s_branch .LBB0_642
.Lkvd_l1:
	global_load_dwordx4 v[222:225], v[4:5], off
	global_load_dwordx4 v[226:229], v[6:7], off
	global_load_dwordx4 v[230:233], v[0:1], off
	global_load_dwordx4 v[234:237], v[2:3], off

; #define MFMA32(a, b, c) __builtin_amdgcn_mfma_f32_32x32x16_bf16((a), (b), (c), 0, 0, 0)
; DI float fexp2(float x) { return __builtin_amdgcn_exp2f(x); }
; template <int KSTRIDE, bool WIN, int MASK, int MODE>
; DI void attend_tile(const u16* Ks, const u16* Vts, const bf16x8 (&qf)[4], f32x16 (&O)[2], float& m, float& l, int dbase,
;                     float slope2, bool lanesel, float invl, unsigned* imp_row, int mbase, int lr, int hh) {
;     ...
;   for (int kt = 0; kt < 2; ++kt) {
; #pragma unroll
;     for (int e = 0; e < 16; ++e) s[kt][e] = 0.f;
; #pragma unroll
;     for (int ks = 0; ks < 4; ++ks) {
;       bf16x8 a = *(const bf16x8*)(Ks + (kt * 32 + lr) * 72 + ks * 16 + hh * 8);
;       s[kt] = MFMA32(a, qf[ks], s[kt]);
;     }
;   }
;   const float fd0 = (float)(dbase - KSTRIDE * 4 * hh);
;   const float ct = slope2 * fd0;
;   float mx = -1e30f;
; #pragma unroll
;   for (int kt = 0; kt < 2; ++kt)
; #pragma unroll
;     for (int e = 0; e < 16; ++e) {
;       const float Ke = (float)(KSTRIDE * (kt * 32 + (e & 3) + 8 * (e >> 2)));
;       float v = fmaf(slope2, Ke, s[kt][e]);
;       if (MASK == 1) {
;         const float fd = fd0 - Ke;
;         bool valid = fd >= 0.f;
;         if (WIN) valid = valid && (fd < 512.f);
;         valid = valid && lanesel;
;         v = valid ? v : -1e30f;
;       }
;       s[kt][e] = v;
;       mx = fmaxf(mx, v);
;     }
;   mx = (mx > -1e29f) ? mx - ct : -1e30f;
;   mx = fmaxf(mx, __shfl_xor(mx, 32));
;   if (MASK == 2) mx = lanesel ? mx : -1e30f;
;   float mnew = m, alpha = 1.f;
;   if (MODE != 2) {
;     mnew = fmaxf(m, mx);
;     alpha = fexp2(m - mnew);
;     m = mnew;
;   }
;   float shift = mnew + ct;
;   if (MASK == 2) shift = lanesel ? shift : 1e30f;
;   float rs = 0.f;
; #pragma unroll
;   for (int kt = 0; kt < 2; ++kt)
; #pragma unroll
;     for (int e = 0; e < 16; ++e) {
;       float v = s[kt][e];
;       float pv;
;       if (MASK == 1) pv = (v > -1e29f) ? fexp2(v - shift) : 0.f;
;       else pv = fexp2(v - shift);
;       if (MODE == 2) pv *= invl;
;       s[kt][e] = pv;
;       rs += pv;
;     }
;   if (MODE != 2) l = l * alpha + rs;
;   if (MODE == 1) return;
;   if (MODE == 0) {
; #pragma unroll
;     for (int e = 0; e < 16; ++e) { O[0][e] *= alpha; O[1][e] *= alpha; }
.LBB0_644:
	s_andn2_b64 vcc, exec, vcc
	s_cbranch_vccnz .LBB0_646
	ds_read_b128 v[16:19], v238 offset:0
	ds_read_b128 v[20:23], v238 offset:32
	ds_read_b128 v[24:27], v238 offset:64
	ds_read_b128 v[28:31], v238 offset:96
	ds_read_b128 v[0:3], v238 offset:128
	ds_read_b128 v[4:7], v238 offset:160
	ds_read_b128 v[8:11], v238 offset:192
	ds_read_b128 v[12:15], v238 offset:224
	s_waitcnt lgkmcnt(4)
	v_mfma_f32_32x32x16_bf16 v[16:31], v[48:51], v[64:67], v[16:31]
	s_lshl_b32 s80, s80, 6
	s_waitcnt lgkmcnt(3)
	v_mfma_f32_32x32x16_bf16 v[16:31], v[44:47], v[68:71], v[16:31]
	s_waitcnt lgkmcnt(2)
	v_mfma_f32_32x32x16_bf16 v[16:31], v[32:35], v[72:75], v[16:31]
	s_waitcnt lgkmcnt(0)
	v_mfma_f32_32x32x16_bf16 v[0:15], v[40:43], v[64:67], v[0:15]
	v_mfma_f32_32x32x16_bf16 v[16:31], v[36:39], v[76:79], v[16:31]
	ds_read_b128 v[32:35], v165 offset:4640
	ds_read_b128 v[36:39], v165 offset:4672
	s_waitcnt lgkmcnt(1)
	v_mfma_f32_32x32x16_bf16 v[0:15], v[32:35], v[68:71], v[0:15]
	ds_read_b128 v[32:35], v165 offset:4704
	s_nop 6
	s_nop 0
	s_nop 0
	s_nop 0
	s_nop 0
	s_nop 0
	s_nop 0
	s_waitcnt lgkmcnt(1)
	v_mfma_f32_32x32x16_bf16 v[0:15], v[36:39], v[72:75], v[0:15]
	s_nop 0
	s_nop 0
	s_nop 0
	s_nop 0
	s_nop 0
	s_nop 0
	s_nop 0
	s_waitcnt lgkmcnt(0)
	v_mfma_f32_32x32x16_bf16 v[0:15], v[32:35], v[76:79], v[0:15]
	v_max3_f32 v33, v16, s95, v17
	v_max3_f32 v33, v33, v18, v19
	v_max3_f32 v33, v33, v20, v21
	v_max3_f32 v33, v33, v22, v23
	v_max3_f32 v33, v33, v24, v25
	v_max3_f32 v33, v33, v26, v27
	s_nop 0
	v_max3_f32 v33, v33, v28, v29
	s_nop 0
	s_nop 0
	v_max3_f32 v33, v33, v30, v31
	s_nop 0
	s_nop 0
	s_nop 0
	v_max3_f32 v33, v33, v0, v1
	s_nop 0
	s_nop 0
	v_max3_f32 v33, v33, v2, v3
	s_nop 0
	s_nop 0
	v_max3_f32 v33, v33, v4, v5
	s_nop 0
	s_nop 0
	v_subrev_u32_e32 v32, s80, v57
	v_max3_f32 v33, v33, v6, v7
	s_nop 0
	s_nop 0
	v_cvt_f32_i32_e32 v32, v32
	v_max3_f32 v33, v33, v8, v9
	s_nop 0
	s_nop 0
	v_max3_f32 v33, v33, v10, v11
	s_nop 0
	s_nop 0
	v_max3_f32 v33, v33, v12, v13
	s_nop 0
	s_nop 0
	v_max3_f32 v33, v33, v14, v15
	v_cmp_lt_f32_e32 vcc, s76, v33
	v_fma_f32 v33, -v106, v32, v33
	s_nop 0
	v_cndmask_b32_e32 v33, v160, v33, vcc
	v_mov_b32_e32 v34, v33
	s_nop 1
	v_permlane32_swap_b32_e32 v34, v33
	s_nop 1
	s_waitcnt lgkmcnt(0)
	v_max_f32_e32 v34, v34, v34
	v_max_f32_e32 v33, v33, v34
	v_cndmask_b32_e64 v33, v160, v33, s[0:1]
	v_max_f32_e32 v34, v169, v169
	v_max_f32_e32 v166, v34, v33
	v_fma_f32 v32, v106, v32, v166
	v_cndmask_b32_e64 v32, v155, v32, s[0:1]
	v_sub_f32_e32 v16, v16, v32
	v_exp_f32_e32 v34, v16
	v_sub_f32_e32 v17, v17, v32
	v_exp_f32_e32 v35, v17
	v_sub_f32_e32 v17, v18, v32
	v_exp_f32_e32 v173, v17
	v_sub_f32_e32 v17, v19, v32
	v_exp_f32_e32 v174, v17
	v_sub_f32_e32 v17, v20, v32
	v_sub_f32_e32 v1, v1, v32
	v_add_f32_e32 v16, 0, v34
	v_exp_f32_e32 v175, v17
	v_sub_f32_e32 v17, v21, v32
	v_exp_f32_e32 v37, v1
	v_sub_f32_e32 v1, v2, v32
	v_add_f32_e32 v16, v35, v16
	v_exp_f32_e32 v176, v17
	v_sub_f32_e32 v17, v22, v32
	v_exp_f32_e32 v38, v1
	v_sub_f32_e32 v1, v3, v32
	v_add_f32_e32 v16, v173, v16
	v_exp_f32_e32 v177, v17
	v_sub_f32_e32 v17, v23, v32
	v_exp_f32_e32 v39, v1
	v_sub_f32_e32 v1, v4, v32
	v_add_f32_e32 v16, v174, v16
	v_exp_f32_e32 v178, v17
	v_sub_f32_e32 v17, v24, v32
	v_exp_f32_e32 v40, v1
	v_sub_f32_e32 v1, v5, v32
	v_add_f32_e32 v16, v175, v16
	v_exp_f32_e32 v51, v17
	v_sub_f32_e32 v17, v25, v32
	v_exp_f32_e32 v41, v1
	v_sub_f32_e32 v1, v6, v32
	v_add_f32_e32 v16, v176, v16
	v_exp_f32_e32 v53, v17
	v_sub_f32_e32 v17, v26, v32
	v_exp_f32_e32 v42, v1
	v_sub_f32_e32 v1, v7, v32
	v_add_f32_e32 v16, v177, v16
	v_exp_f32_e32 v54, v17
	v_sub_f32_e32 v17, v27, v32
	v_exp_f32_e32 v44, v1
	v_sub_f32_e32 v1, v8, v32
	v_add_f32_e32 v16, v178, v16
	v_exp_f32_e32 v55, v17
	v_sub_f32_e32 v17, v28, v32
	v_exp_f32_e32 v43, v1
	v_sub_f32_e32 v1, v9, v32
	v_sub_f32_e32 v33, v169, v166
	v_add_f32_e32 v16, v51, v16
	v_exp_f32_e32 v169, v17
	v_sub_f32_e32 v17, v29, v32
	v_exp_f32_e32 v45, v1
	v_sub_f32_e32 v1, v10, v32
	v_add_f32_e32 v16, v53, v16
	v_exp_f32_e32 v170, v17
	v_sub_f32_e32 v17, v30, v32
	v_exp_f32_e32 v46, v1
	v_sub_f32_e32 v1, v11, v32
	v_add_f32_e32 v16, v54, v16
	v_exp_f32_e32 v171, v17
	v_sub_f32_e32 v17, v31, v32
	v_exp_f32_e32 v47, v1
	v_sub_f32_e32 v1, v12, v32
	v_add_f32_e32 v16, v55, v16
	v_exp_f32_e32 v172, v17
	v_sub_f32_e32 v0, v0, v32
	v_exp_f32_e32 v48, v1
	v_sub_f32_e32 v1, v13, v32
	v_add_f32_e32 v16, v169, v16
	v_exp_f32_e32 v36, v0
	v_exp_f32_e32 v49, v1
	v_sub_f32_e32 v1, v14, v32
	v_exp_f32_e32 v14, v33
	v_add_f32_e32 v16, v170, v16
	v_add_f32_e32 v16, v171, v16
	v_add_f32_e32 v16, v172, v16
	v_add_f32_e32 v0, v36, v16
	v_pk_mul_f32 v[16:17], v[122:123], v[14:15] op_sel_hi:[1,0]
	v_pk_mul_f32 v[18:19], v[124:125], v[14:15] op_sel_hi:[1,0]
	ds_read_b128 v[122:125], v165 offset:9216
	v_add_f32_e32 v0, v37, v0
	v_add_f32_e32 v0, v38, v0
	v_add_f32_e32 v0, v39, v0
	v_add_f32_e32 v0, v40, v0
	v_add_f32_e32 v0, v41, v0
	v_add_f32_e32 v0, v42, v0
	v_add_f32_e32 v0, v44, v0
	v_exp_f32_e32 v50, v1
	v_sub_f32_e32 v1, v15, v32
	v_pk_mul_f32 v[20:21], v[126:127], v[14:15] op_sel_hi:[1,0]
	v_pk_mul_f32 v[22:23], v[128:129], v[14:15] op_sel_hi:[1,0]
	v_pk_mul_f32 v[24:25], v[130:131], v[14:15] op_sel_hi:[1,0]
	v_pk_mul_f32 v[26:27], v[132:133], v[14:15] op_sel_hi:[1,0]
	v_pk_mul_f32 v[28:29], v[134:135], v[14:15] op_sel_hi:[1,0]
	v_pk_mul_f32 v[30:31], v[136:137], v[14:15] op_sel_hi:[1,0]
	v_cvt_pk_bf16_f32 v32, v34, v35
	v_cvt_pk_bf16_f32 v33, v173, v174
	v_cvt_pk_bf16_f32 v34, v175, v176
	v_cvt_pk_bf16_f32 v35, v177, v178
	v_add_f32_e32 v0, v43, v0
	v_add_f32_e32 v0, v45, v0
	s_waitcnt lgkmcnt(0)
; #define MFMA32(a, b, c) __builtin_amdgcn_mfma_f32_32x32x16_bf16((a), (b), (c), 0, 0, 0)
; template <int KSTRIDE, bool WIN, int MASK, int MODE>
; DI void attend_tile(const u16* Ks, const u16* Vts, const bf16x8 (&qf)[4], f32x16 (&O)[2], float& m, float& l, int dbase,
;                     float slope2, bool lanesel, float invl, unsigned* imp_row, int mbase, int lr, int hh) {
;     ...
; #pragma unroll
;   for (int kt = 0; kt < 2; ++kt)
; #pragma unroll
;     for (int sx = 0; sx < 2; ++sx) {
;       unsigned pk[4];
; #pragma unroll
;       for (int q = 0; q < 4; ++q) pk[q] = pack2(s[kt][8 * sx + 2 * q], s[kt][8 * sx + 2 * q + 1]);
;       bf16x8 pb;
;       {
;         u32x4 t4 = {pk[0], pk[1], pk[2], pk[3]};
;         pb = __builtin_bit_cast(bf16x8, t4);
;       }
; #pragma unroll
;       for (int dt = 0; dt < 2; ++dt) {
;         bf16x8 a = *(const bf16x8*)(Vts + (dt * 32 + lr) * 72 + kt * 32 + 16 * sx + 8 * hh);
;         O[dt] = MFMA32(a, pb, O[dt]);
;       }
;     }
; DI void attn_item(const Params& p, int item, char* smem) {
;     ...
;     while (j >= 0) {
;       kv_commit(kvr, Ks, Vts, tid);
;       int jn = -1;
;       if (am) { jn = __builtin_ctzll(am); am &= am - 1; }
;       if (jn >= 0) kv_issue(kvr, KS + ((size_t)(b * 4096 + 64 * jn)) * 128 + g * 64, 128, VTS + (size_t)bg * 64 * 4096 + 64 * jn, 4096, tid);
;       bool ls = (j < 32) ? ((mylo >> j) & 1u) : ((myhi >> (j - 32)) & 1u);
;       if (j < qb) attend_tile<1, false, 2, 0>(Ks, Vts, qf, O, m, l, t - 64 * j, slope2, ls, 0.f, nullptr, 0, lr, hh);
;       else attend_tile<1, false, 1, 0>(Ks, Vts, qf, O, m, l, t - 64 * j, slope2, ls, 0.f, nullptr, 0, lr, hh);
;       pb ^= 1;
;       j = jn;
;     }
	v_mfma_f32_32x32x16_bf16 v[16:31], v[122:125], v[32:35], v[16:31]
	ds_read_b128 v[122:125], v165 offset:13824
	v_add_f32_e32 v0, v46, v0
	v_add_f32_e32 v0, v47, v0
	v_exp_f32_e32 v52, v1
	v_add_f32_e32 v0, v48, v0
	v_add_f32_e32 v0, v49, v0
	v_add_f32_e32 v0, v50, v0
	v_add_f32_e32 v167, v52, v0
	v_fmac_f32_e32 v167, v168, v14
	v_pk_mul_f32 v[0:1], v[138:139], v[14:15] op_sel_hi:[1,0]
	v_pk_mul_f32 v[2:3], v[140:141], v[14:15] op_sel_hi:[1,0]
	v_pk_mul_f32 v[4:5], v[142:143], v[14:15] op_sel_hi:[1,0]
	v_pk_mul_f32 v[6:7], v[144:145], v[14:15] op_sel_hi:[1,0]
	v_pk_mul_f32 v[8:9], v[146:147], v[14:15] op_sel_hi:[1,0]
	v_pk_mul_f32 v[10:11], v[148:149], v[14:15] op_sel_hi:[1,0]
	v_pk_mul_f32 v[12:13], v[150:151], v[14:15] op_sel_hi:[1,0]
	v_pk_mul_f32 v[14:15], v[152:153], v[14:15] op_sel_hi:[1,0]
	s_waitcnt lgkmcnt(0)
	s_nop 0
	v_mfma_f32_32x32x16_bf16 v[0:15], v[122:125], v[32:35], v[0:15]
	ds_read_b128 v[122:125], v165 offset:9248
	v_cvt_pk_bf16_f32 v32, v51, v53
	v_cvt_pk_bf16_f32 v33, v54, v55
	v_cvt_pk_bf16_f32 v34, v169, v170
	v_cvt_pk_bf16_f32 v35, v171, v172
	s_waitcnt lgkmcnt(0)
	s_nop 0
	v_mfma_f32_32x32x16_bf16 v[16:31], v[122:125], v[32:35], v[16:31]
	ds_read_b128 v[122:125], v165 offset:13856
	s_waitcnt lgkmcnt(0)
	v_mfma_f32_32x32x16_bf16 v[0:15], v[122:125], v[32:35], v[0:15]
	v_cvt_pk_bf16_f32 v32, v36, v37
	v_cvt_pk_bf16_f32 v33, v38, v39
	ds_read_b128 v[36:39], v165 offset:9280
	v_cvt_pk_bf16_f32 v34, v40, v41
	v_cvt_pk_bf16_f32 v35, v42, v44
	s_waitcnt lgkmcnt(0)
	s_nop 0
	v_mfma_f32_32x32x16_bf16 v[16:31], v[36:39], v[32:35], v[16:31]
	ds_read_b128 v[36:39], v165 offset:13888
	s_waitcnt lgkmcnt(0)
	v_mfma_f32_32x32x16_bf16 v[0:15], v[36:39], v[32:35], v[0:15]
	ds_read_b128 v[36:39], v165 offset:9312
	v_cvt_pk_bf16_f32 v32, v43, v45
	v_cvt_pk_bf16_f32 v33, v46, v47
	v_cvt_pk_bf16_f32 v34, v48, v49
	v_cvt_pk_bf16_f32 v35, v50, v52
	s_waitcnt lgkmcnt(0)
	s_nop 0
	v_mfma_f32_32x32x16_bf16 v[16:31], v[36:39], v[32:35], v[16:31]
	ds_read_b128 v[36:39], v165 offset:13920
	s_waitcnt lgkmcnt(0)
	v_mfma_f32_32x32x16_bf16 v[0:15], v[36:39], v[32:35], v[0:15]
.LBB0_646:
	s_add_u32 s0, s88, -1
	s_addc_u32 s1, s89, -1
	s_and_b64 s[88:89], s[0:1], s[88:89]
	s_andn2_b64 vcc, exec, s[90:91]
	s_xor_b32 s79, s79, 1
	s_cbranch_vccz .LBB0_611
	v_mov_b32_e32 v168, v167
	s_mov_b32 s80, s92
	v_mov_b32_e32 v169, v166
	v_mov_b32_e32 v122, v16
	v_mov_b32_e32 v123, v17
	v_mov_b32_e32 v124, v18
	v_mov_b32_e32 v125, v19
	v_mov_b32_e32 v126, v20
	v_mov_b32_e32 v127, v21
	v_mov_b32_e32 v128, v22
	v_mov_b32_e32 v129, v23
	v_mov_b32_e32 v130, v24
	v_mov_b32_e32 v131, v25
	v_mov_b32_e32 v132, v26
	v_mov_b32_e32 v133, v27
	v_mov_b32_e32 v134, v28
	v_mov_b32_e32 v135, v29
	v_mov_b32_e32 v136, v30
	v_mov_b32_e32 v137, v31
	v_mov_b32_e32 v138, v0
	v_mov_b32_e32 v139, v1
	v_mov_b32_e32 v140, v2
	v_mov_b32_e32 v141, v3
	v_mov_b32_e32 v142, v4
	v_mov_b32_e32 v143, v5
	v_mov_b32_e32 v144, v6
	v_mov_b32_e32 v145, v7
	v_mov_b32_e32 v146, v8
	v_mov_b32_e32 v147, v9
	v_mov_b32_e32 v148, v10
	v_mov_b32_e32 v149, v11
	v_mov_b32_e32 v150, v12
	v_mov_b32_e32 v151, v13
	v_mov_b32_e32 v152, v14
	v_mov_b32_e32 v153, v15
	s_waitcnt vmcnt(4)
	s_cmp_eq_u32 s79, 0
	s_cbranch_scc0 .Lkvd_m1
	v_mov_b32_e32 v80, v200
	v_mov_b32_e32 v81, v201
	v_mov_b32_e32 v82, v202
	v_mov_b32_e32 v83, v203
	v_mov_b32_e32 v84, v204
	v_mov_b32_e32 v85, v205
	v_mov_b32_e32 v86, v206
	v_mov_b32_e32 v87, v207
	v_mov_b32_e32 v88, v214
	v_mov_b32_e32 v89, v215
	v_mov_b32_e32 v90, v216
	v_mov_b32_e32 v91, v217
	v_mov_b32_e32 v92, v218
	v_mov_b32_e32 v93, v219
	v_mov_b32_e32 v94, v220
	v_mov_b32_e32 v95, v221
	s_branch .LBB0_631
.Lkvd_m1:
	v_mov_b32_e32 v80, v222
	v_mov_b32_e32 v81, v223
	v_mov_b32_e32 v82, v224
	v_mov_b32_e32 v83, v225
	v_mov_b32_e32 v84, v226
	v_mov_b32_e32 v85, v227
	v_mov_b32_e32 v86, v228
	v_mov_b32_e32 v87, v229
	v_mov_b32_e32 v88, v230
	v_mov_b32_e32 v89, v231
	v_mov_b32_e32 v90, v232
	v_mov_b32_e32 v91, v233
	v_mov_b32_e32 v92, v234
	v_mov_b32_e32 v93, v235
	v_mov_b32_e32 v94, v236
	v_mov_b32_e32 v95, v237
	s_branch .LBB0_631

; __global__ void __launch_bounds__(512) fwd_megakernel(Params p) {
;   extern __shared__ __attribute__((aligned(16))) char smem[];
	.amdhsa_kernel _Z14fwd_megakernel6Params
		.amdhsa_group_segment_fixed_size 32
		.amdhsa_private_segment_fixed_size 0
		.amdhsa_kernarg_size 448
		.amdhsa_user_sgpr_count 2
		.amdhsa_user_sgpr_dispatch_ptr 0
		.amdhsa_user_sgpr_queue_ptr 0
		.amdhsa_user_sgpr_kernarg_segment_ptr 1
		.amdhsa_user_sgpr_dispatch_id 0
		.amdhsa_user_sgpr_kernarg_preload_length 0
		.amdhsa_user_sgpr_kernarg_preload_offset 0
		.amdhsa_user_sgpr_private_segment_size 0
		.amdhsa_uses_dynamic_stack 0
		.amdhsa_enable_private_segment 0
		.amdhsa_system_sgpr_workgroup_id_x 1
		.amdhsa_system_sgpr_workgroup_id_y 0
		.amdhsa_system_sgpr_workgroup_id_z 0
		.amdhsa_system_sgpr_workgroup_info 0
		.amdhsa_system_vgpr_workitem_id 2
		.amdhsa_next_free_vgpr 255
		.amdhsa_next_free_sgpr 102
		.amdhsa_accum_offset 256
		.amdhsa_reserve_vcc 1
		.amdhsa_float_round_mode_32 0
		.amdhsa_float_round_mode_16_64 0
		.amdhsa_float_denorm_mode_32 3
		.amdhsa_float_denorm_mode_16_64 3
		.amdhsa_dx10_clamp 1
		.amdhsa_ieee_mode 1
		.amdhsa_fp16_overflow 0
		.amdhsa_tg_split 0
		.amdhsa_exception_fp_ieee_invalid_op 0
		.amdhsa_exception_fp_denorm_src 0
		.amdhsa_exception_fp_ieee_div_zero 0
		.amdhsa_exception_fp_ieee_overflow 0
		.amdhsa_exception_fp_ieee_underflow 0
		.amdhsa_exception_fp_ieee_inexact 0
		.amdhsa_exception_int_div_zero 0
	.end_amdhsa_kernel

; __global__ void __launch_bounds__(512) fwd_megakernel(Params p) {
;   extern __shared__ __attribute__((aligned(16))) char smem[];
.Lfunc_end0:
	.size	_Z14fwd_megakernel6Params, .Lfunc_end0-_Z14fwd_megakernel6Params
	.set _Z14fwd_megakernel6Params.num_vgpr, 255
	.set _Z14fwd_megakernel6Params.num_agpr, 0
	.set _Z14fwd_megakernel6Params.numbered_sgpr, 102
	.set _Z14fwd_megakernel6Params.num_named_barrier, 0
	.set _Z14fwd_megakernel6Params.private_seg_size, 0
	.set _Z14fwd_megakernel6Params.uses_vcc, 1
	.set _Z14fwd_megakernel6Params.uses_flat_scratch, 0
	.set _Z14fwd_megakernel6Params.has_dyn_sized_stack, 0
	.set _Z14fwd_megakernel6Params.has_recursion, 0
	.set _Z14fwd_megakernel6Params.has_indirect_call, 0

; __global__ void __launch_bounds__(512) fwd_megakernel(Params p) {
;   extern __shared__ __attribute__((aligned(16))) char smem[];
amdhsa.kernels:
  - .agpr_count:     0
    .args:
      - .offset:         0
        .size:           192
        .value_kind:     by_value
      - .offset:         192
        .size:           4
        .value_kind:     hidden_block_count_x
      - .offset:         196
        .size:           4
        .value_kind:     hidden_block_count_y
      - .offset:         200
        .size:           4
        .value_kind:     hidden_block_count_z
      - .offset:         204
        .size:           2
        .value_kind:     hidden_group_size_x
      - .offset:         206
        .size:           2
        .value_kind:     hidden_group_size_y
      - .offset:         208
        .size:           2
        .value_kind:     hidden_group_size_z
      - .offset:         210
        .size:           2
        .value_kind:     hidden_remainder_x
      - .offset:         212
        .size:           2
        .value_kind:     hidden_remainder_y
      - .offset:         214
        .size:           2
        .value_kind:     hidden_remainder_z
      - .offset:         232
        .size:           8
        .value_kind:     hidden_global_offset_x
      - .offset:         240
        .size:           8
        .value_kind:     hidden_global_offset_y
      - .offset:         248
        .size:           8
        .value_kind:     hidden_global_offset_z
      - .offset:         256
        .size:           2
        .value_kind:     hidden_grid_dims
      - .offset:         280
        .size:           8
        .value_kind:     hidden_multigrid_sync_arg
      - .offset:         312
        .size:           4
        .value_kind:     hidden_dynamic_lds_size
    .group_segment_fixed_size: 32
    .kernarg_segment_align: 8
    .kernarg_segment_size: 448
    .language:       OpenCL C
    .language_version:
      - 2
      - 0
    .max_flat_workgroup_size: 512
    .name:           _Z14fwd_megakernel6Params
    .private_segment_fixed_size: 0
    .sgpr_count:     108
    .sgpr_spill_count: 75
    .symbol:         _Z14fwd_megakernel6Params.kd
    .uniform_work_group_size: 1
    .uses_dynamic_stack: false
    .vgpr_count:     255
    .vgpr_spill_count: 0
    .wavefront_size: 64
